# grid barrier: non-leader workgroups poll the global release flag directly instead of the per-XCD relay flag
# speedup vs baseline: 1.0064x; 1.0064x over previous
; DI unsigned xb_ld(unsigned* p) { return __hip_atomic_load(p, __ATOMIC_RELAXED, __HIP_MEMORY_SCOPE_AGENT); }
; DI unsigned xb_add(unsigned* p, unsigned v) { return __hip_atomic_fetch_add(p, v, __ATOMIC_RELAXED, __HIP_MEMORY_SCOPE_AGENT); }
; DI void xcd_barrier(const XcdBarrier& b) {
;     ...
;     const unsigned old = xb_add(&bar[XB_XSUB(bx)], 1u);
;     const unsigned gen = old / nloc;
;     if (old + 1u == (gen + 1u) * nloc) {
;       __builtin_amdgcn_fence(__ATOMIC_RELEASE, "agent");
;       asm volatile("s_waitcnt vmcnt(0)" ::: "memory");
;       const unsigned og = xb_add(&bar[XB_TOP], 1u);
;       const unsigned tg = og / nx;
;       if (og + 1u == (tg + 1u) * nx) xb_add(&bar[XB_TOPGEN], 1u);
;       else { while (xb_ld(&bar[XB_TOPGEN]) == tg) __builtin_amdgcn_s_sleep(1); }
;       __builtin_amdgcn_fence(__ATOMIC_ACQUIRE, "agent");
;       xb_add(&bar[XB_XGEN(bx)], 1u);
;       asm volatile("s_waitcnt vmcnt(0)" ::: "memory");
;     } else {
;       while (xb_ld(&bar[XB_XGEN(bx)]) == gen) __builtin_amdgcn_s_sleep(1);
;       __builtin_amdgcn_fence(__ATOMIC_ACQUIRE, "agent");
.LBB0_893:
	s_or_b64 exec, exec, s[4:5]
	v_cvt_f32_u32_e32 v5, v2
	s_waitcnt vmcnt(0)
	v_readfirstlane_b32 s2, v4
	v_sub_u32_e32 v4, 0, v2
	v_rcp_iflag_f32_e32 v5, v5
	v_add_u32_e32 v6, s2, v3
	v_mul_f32_e32 v5, 0x4f7ffffe, v5
	v_cvt_u32_f32_e32 v5, v5
	v_mul_lo_u32 v3, v4, v5
	v_mul_hi_u32 v3, v5, v3
	v_add_u32_e32 v3, v5, v3
	v_mul_hi_u32 v3, v6, v3
	v_mul_lo_u32 v4, v3, v2
	v_sub_u32_e32 v4, v6, v4
	v_add_u32_e32 v5, 1, v3
	v_cmp_ge_u32_e32 vcc, v4, v2
	s_nop 1
	v_cndmask_b32_e32 v3, v3, v5, vcc
	v_sub_u32_e32 v5, v4, v2
	v_cndmask_b32_e32 v4, v4, v5, vcc
	v_add_u32_e32 v5, 1, v3
	v_cmp_ge_u32_e32 vcc, v4, v2
	v_add_u32_e32 v4, 1, v6
	s_nop 0
	v_cndmask_b32_e32 v3, v3, v5, vcc
	v_mul_lo_u32 v5, v2, v3
	v_add_u32_e32 v2, v5, v2
	v_cmp_ne_u32_e32 vcc, v4, v2
	s_and_saveexec_b64 s[2:3], vcc
	s_xor_b64 s[2:3], exec, s[2:3]
	s_cbranch_execz .LBB0_898
	v_readlane_b32 s4, v252, 35
	v_readlane_b32 s5, v252, 36
	s_mov_b32 s7, s5
	v_writelane_b32 v252, s4, 35
	s_add_i32 s6, s10, 0x900
	s_nop 0
	v_writelane_b32 v252, s5, 36
	s_lshl_b64 s[4:5], s[6:7], 2
	v_readlane_b32 s6, v252, 16
	v_readlane_b32 s7, v252, 17
	s_add_u32 s4, s6, s4
	s_addc_u32 s5, s7, s5
	s_mov_b64 s[4:5], s[50:51]
	s_waitcnt lgkmcnt(0)
	global_load_dword v0, v1, s[4:5] sc1
	s_waitcnt vmcnt(0)
	v_cmp_eq_u32_e32 vcc, v0, v3
	s_and_saveexec_b64 s[6:7], vcc
	s_cbranch_execz .LBB0_897
	s_mov_b64 s[8:9], 0
